# v013 plus grid-barrier L1 invalidate issued before the spin (hidden behind the wait) instead of after the release is observed
# baseline (speedup 1.0000x reference)
; __device__ __forceinline__ unsigned xb_ld(unsigned* p)              { return __hip_atomic_load(p, __ATOMIC_RELAXED, __HIP_MEMORY_SCOPE_AGENT); }
; __device__ __forceinline__ unsigned xb_add(unsigned* p, unsigned v) { return __hip_atomic_fetch_add(p, v, __ATOMIC_RELAXED, __HIP_MEMORY_SCOPE_AGENT); }
; #define XB_SPIN(cond, bar) do { unsigned _sp = 0; while (cond) { __builtin_amdgcn_s_sleep(1); \
;     if ((++_sp & 255u) == 0u) { if (xb_ld(&(bar)[XB_TMO])) break; if (_sp > XB_SPIN_CAP) { atomicAdd(&(bar)[XB_TMO], 1u); break; } } } } while (0)
; __device__ __forceinline__ void xcd_barrier(const XcdBarrier& b) {
;     ...
;         const unsigned old = xb_add(&bar[XB_XSUB(b.x)], 1u);
;         const unsigned gen = old / nloc;
;         if (old + 1u == (gen + 1u) * nloc) {
;             __builtin_amdgcn_fence(__ATOMIC_RELEASE, "agent");
;             asm volatile("s_waitcnt vmcnt(0)" ::: "memory");
;             const unsigned og = xb_add(&bar[XB_TOP], 1u);
;             const unsigned tg = og / nx;
;             if (og + 1u == (tg + 1u) * nx) xb_add(&bar[XB_TOPGEN], 1u);
;             else XB_SPIN(xb_ld(&bar[XB_TOPGEN]) == tg, bar);
.LBB0_128:
	s_andn2_saveexec_b64 s[2:3], s[4:5]
	s_cbranch_execz .LBB0_144
	v_add_co_u32_e32 v6, vcc, 0x3000, v0
	buffer_wbl2 sc1
	buffer_inv sc1
	s_waitcnt lgkmcnt(0)
	s_waitcnt vmcnt(0)
	v_addc_co_u32_e32 v7, vcc, 0, v1, vcc
	v_mov_b32_e32 v5, 1
	global_atomic_add v5, v[6:7], v5, off offset:1024 sc0
	v_cvt_f32_u32_e32 v6, v4
	v_sub_u32_e32 v8, 0, v4
	s_mov_b64 s[2:3], 0x3500
	s_mov_b64 s[6:7], -1
	v_rcp_iflag_f32_e32 v6, v6
	s_nop 0
	v_mul_f32_e32 v6, 0x4f7ffffe, v6
	v_cvt_u32_f32_e32 v9, v6
	v_lshl_add_u64 v[6:7], v[0:1], 0, s[2:3]
	v_mul_lo_u32 v8, v8, v9
	v_mul_hi_u32 v8, v9, v8
	v_add_u32_e32 v8, v9, v8
	s_waitcnt vmcnt(0)
	v_mul_hi_u32 v8, v5, v8
	v_mul_lo_u32 v10, v8, v4
	v_add_u32_e32 v9, 1, v5
	v_sub_u32_e32 v5, v5, v10
	v_add_u32_e32 v11, 1, v8
	v_cmp_ge_u32_e32 vcc, v5, v4
	v_sub_u32_e32 v10, v5, v4
	s_nop 0
	v_cndmask_b32_e32 v8, v8, v11, vcc
	v_cndmask_b32_e32 v5, v5, v10, vcc
	v_add_u32_e32 v10, 1, v8
	v_cmp_ge_u32_e32 vcc, v5, v4
	s_nop 1
	v_cndmask_b32_e32 v8, v8, v10, vcc
	v_mad_u64_u32 v[4:5], s[2:3], v4, v8, v[4:5]
	v_cmp_ne_u32_e32 vcc, v9, v4
	s_and_saveexec_b64 s[4:5], vcc
	s_cbranch_execz .LBB0_141
	global_load_dword v4, v[6:7], off sc1
	s_mov_b64 s[8:9], 0
	s_waitcnt vmcnt(0)
	v_cmp_eq_u32_e32 vcc, v4, v8
	s_and_saveexec_b64 s[6:7], vcc
	s_cbranch_execz .LBB0_140
	s_mov_b64 s[2:3], 0x200
	v_lshl_add_u64 v[4:5], v[0:1], 0, s[2:3]
	s_mov_b32 s1, 1
	s_branch .LBB0_133

; __device__ __forceinline__ unsigned xb_ld(unsigned* p)              { return __hip_atomic_load(p, __ATOMIC_RELAXED, __HIP_MEMORY_SCOPE_AGENT); }
; __device__ __forceinline__ unsigned xb_add(unsigned* p, unsigned v) { return __hip_atomic_fetch_add(p, v, __ATOMIC_RELAXED, __HIP_MEMORY_SCOPE_AGENT); }
; #define XB_SPIN(cond, bar) do { unsigned _sp = 0; while (cond) { __builtin_amdgcn_s_sleep(1); \
;     if ((++_sp & 255u) == 0u) { if (xb_ld(&(bar)[XB_TMO])) break; if (_sp > XB_SPIN_CAP) { atomicAdd(&(bar)[XB_TMO], 1u); break; } } } } while (0)
; __device__ __forceinline__ void xcd_barrier(const XcdBarrier& b) {
;     ...
;             else XB_SPIN(xb_ld(&bar[XB_TOPGEN]) == tg, bar);
;             __builtin_amdgcn_fence(__ATOMIC_ACQUIRE, "agent");
;             xb_add(&bar[XB_XGEN(b.x)], 1u);
.LBB0_143:
	s_or_b64 exec, exec, s[4:5]
	v_add_co_u32_e32 v0, vcc, 0x2000, v2
	v_mov_b32_e32 v2, 1
	s_nop 0
	v_addc_co_u32_e32 v1, vcc, 0, v3, vcc
	s_waitcnt vmcnt(0)
	global_atomic_add v[0:1], v2, off offset:1024
	s_waitcnt vmcnt(0)

; __device__ __forceinline__ unsigned xb_add(unsigned* p, unsigned v) { return __hip_atomic_fetch_add(p, v, __ATOMIC_RELAXED, __HIP_MEMORY_SCOPE_AGENT); }
; __device__ __forceinline__ void xcd_barrier(const XcdBarrier& b) {
;     ...
;         if (old + 1u == (gen + 1u) * nloc) {
;             __builtin_amdgcn_fence(__ATOMIC_RELEASE, "agent");
;             asm volatile("s_waitcnt vmcnt(0)" ::: "memory");
;             const unsigned og = xb_add(&bar[XB_TOP], 1u);
.LBB0_180:
	s_andn2_saveexec_b64 s[10:11], s[10:11]
	s_cbranch_execz .LBB0_200
	s_mov_b64 s[12:13], exec
	buffer_wbl2 sc1
	buffer_inv sc1
	s_waitcnt lgkmcnt(0)
	s_waitcnt vmcnt(0)
	v_mbcnt_lo_u32_b32 v1, s12, 0
	v_mbcnt_hi_u32_b32 v1, s13, v1
	v_cmp_eq_u32_e32 vcc, 0, v1
	s_and_saveexec_b64 s[14:15], vcc
	s_cbranch_execz .LBB0_183
	s_bcnt1_i32_b64 s1, s[12:13]
	v_mov_b32_e32 v2, 0x3000
	v_mov_b32_e32 v3, s1
	global_atomic_add v2, v2, v3, s[6:7] offset:1024 sc0

; __device__ __forceinline__ unsigned xb_ld(unsigned* p)              { return __hip_atomic_load(p, __ATOMIC_RELAXED, __HIP_MEMORY_SCOPE_AGENT); }
; __device__ __forceinline__ unsigned xb_add(unsigned* p, unsigned v) { return __hip_atomic_fetch_add(p, v, __ATOMIC_RELAXED, __HIP_MEMORY_SCOPE_AGENT); }
; #define XB_SPIN(cond, bar) do { unsigned _sp = 0; while (cond) { __builtin_amdgcn_s_sleep(1); \
;     if ((++_sp & 255u) == 0u) { if (xb_ld(&(bar)[XB_TMO])) break; if (_sp > XB_SPIN_CAP) { atomicAdd(&(bar)[XB_TMO], 1u); break; } } } } while (0)
; __device__ __forceinline__ void xcd_barrier(const XcdBarrier& b) {
;     ...
;             else XB_SPIN(xb_ld(&bar[XB_TOPGEN]) == tg, bar);
;             __builtin_amdgcn_fence(__ATOMIC_ACQUIRE, "agent");
;             xb_add(&bar[XB_XGEN(b.x)], 1u);
.LBB0_197:
	s_or_b64 exec, exec, s[6:7]
	s_mov_b64 s[6:7], exec
	v_mbcnt_lo_u32_b32 v0, s6, 0
	v_mbcnt_hi_u32_b32 v0, s7, v0
	v_cmp_eq_u32_e32 vcc, 0, v0
	s_waitcnt vmcnt(0)
	s_and_saveexec_b64 s[12:13], vcc
	s_cbranch_execz .LBB0_199
	s_bcnt1_i32_b64 s1, s[6:7]
	v_mov_b32_e32 v0, 0x2000
	v_mov_b32_e32 v1, s1
	global_atomic_add v0, v1, s[8:9] offset:1024

; __device__ __forceinline__ unsigned xb_ld(unsigned* p)              { return __hip_atomic_load(p, __ATOMIC_RELAXED, __HIP_MEMORY_SCOPE_AGENT); }
; __device__ __forceinline__ unsigned xb_add(unsigned* p, unsigned v) { return __hip_atomic_fetch_add(p, v, __ATOMIC_RELAXED, __HIP_MEMORY_SCOPE_AGENT); }
; #define XB_SPIN(cond, bar) do { unsigned _sp = 0; while (cond) { __builtin_amdgcn_s_sleep(1); \
;     if ((++_sp & 255u) == 0u) { if (xb_ld(&(bar)[XB_TMO])) break; if (_sp > XB_SPIN_CAP) { atomicAdd(&(bar)[XB_TMO], 1u); break; } } } } while (0)
; __device__ __forceinline__ void xcd_barrier(const XcdBarrier& b) {
;     ...
;         const unsigned old = xb_add(&bar[XB_XSUB(b.x)], 1u);
;         const unsigned gen = old / nloc;
;         if (old + 1u == (gen + 1u) * nloc) {
;     ...
;             XB_SPIN(xb_ld(&bar[XB_XGEN(b.x)]) == gen, bar);
;             __builtin_amdgcn_fence(__ATOMIC_ACQUIRE, "agent");
;             asm volatile("s_waitcnt vmcnt(0)" ::: "memory");
.LBB0_241:
	s_or_b64 exec, exec, s[12:13]
	v_cvt_f32_u32_e32 v4, v2
	s_waitcnt vmcnt(0)
	v_readfirstlane_b32 s0, v3
	v_sub_u32_e32 v3, 0, v2
	v_rcp_iflag_f32_e32 v4, v4
	v_add_u32_e32 v5, s0, v1
	v_mul_f32_e32 v4, 0x4f7ffffe, v4
	v_cvt_u32_f32_e32 v4, v4
	v_mul_lo_u32 v1, v3, v4
	v_mul_hi_u32 v1, v4, v1
	v_add_u32_e32 v1, v4, v1
	v_mul_hi_u32 v1, v5, v1
	v_mul_lo_u32 v3, v1, v2
	v_sub_u32_e32 v3, v5, v3
	v_add_u32_e32 v4, 1, v1
	v_cmp_ge_u32_e32 vcc, v3, v2
	s_nop 1
	v_cndmask_b32_e32 v1, v1, v4, vcc
	v_sub_u32_e32 v4, v3, v2
	v_cndmask_b32_e32 v3, v3, v4, vcc
	v_add_u32_e32 v4, 1, v1
	v_cmp_ge_u32_e32 vcc, v3, v2
	v_add_u32_e32 v3, 1, v5
	s_nop 0
	v_cndmask_b32_e32 v1, v1, v4, vcc
	v_mul_lo_u32 v4, v2, v1
	v_add_u32_e32 v2, v4, v2
	v_cmp_ne_u32_e32 vcc, v3, v2
	s_and_saveexec_b64 s[0:1], vcc
	s_xor_b64 s[10:11], exec, s[0:1]
	s_cbranch_execz .LBB0_255
	buffer_inv sc1
	s_waitcnt lgkmcnt(0)
	global_load_dword v0, v226, s[8:9] offset:1024 sc1
	s_add_u32 s14, s8, 0x2400
	s_addc_u32 s15, s9, 0
	s_waitcnt vmcnt(0)
	v_cmp_eq_u32_e32 vcc, v0, v1
	s_and_saveexec_b64 s[12:13], vcc
	s_cbranch_execz .LBB0_254
	s_mov_b32 s0, 1
	s_mov_b64 s[16:17], 0
	s_branch .LBB0_245

; __device__ __forceinline__ unsigned xb_ld(unsigned* p)              { return __hip_atomic_load(p, __ATOMIC_RELAXED, __HIP_MEMORY_SCOPE_AGENT); }
; __device__ __forceinline__ unsigned xb_add(unsigned* p, unsigned v) { return __hip_atomic_fetch_add(p, v, __ATOMIC_RELAXED, __HIP_MEMORY_SCOPE_AGENT); }
; #define XB_SPIN(cond, bar) do { unsigned _sp = 0; while (cond) { __builtin_amdgcn_s_sleep(1); \
;     if ((++_sp & 255u) == 0u) { if (xb_ld(&(bar)[XB_TMO])) break; if (_sp > XB_SPIN_CAP) { atomicAdd(&(bar)[XB_TMO], 1u); break; } } } } while (0)
; __device__ __forceinline__ void xcd_barrier(const XcdBarrier& b) {
;     ...
;         if (old + 1u == (gen + 1u) * nloc) {
;             __builtin_amdgcn_fence(__ATOMIC_RELEASE, "agent");
;             asm volatile("s_waitcnt vmcnt(0)" ::: "memory");
;             const unsigned og = xb_add(&bar[XB_TOP], 1u);
;             const unsigned tg = og / nx;
;             if (og + 1u == (tg + 1u) * nx) xb_add(&bar[XB_TOPGEN], 1u);
;             else XB_SPIN(xb_ld(&bar[XB_TOPGEN]) == tg, bar);
;             __builtin_amdgcn_fence(__ATOMIC_ACQUIRE, "agent");
;             xb_add(&bar[XB_XGEN(b.x)], 1u);
;             asm volatile("s_waitcnt vmcnt(0)" ::: "memory");
;         } else {
;             XB_SPIN(xb_ld(&bar[XB_XGEN(b.x)]) == gen, bar);
;             __builtin_amdgcn_fence(__ATOMIC_ACQUIRE, "agent");
;             asm volatile("s_waitcnt vmcnt(0)" ::: "memory");
.LBB0_254:
	s_or_b64 exec, exec, s[12:13]
	s_waitcnt vmcnt(0)
	s_waitcnt vmcnt(0)
.LBB0_255:
	s_andn2_saveexec_b64 s[0:1], s[10:11]
	s_cbranch_execz .LBB0_275
	s_mov_b64 s[10:11], exec
	buffer_wbl2 sc1
	buffer_inv sc1
	s_waitcnt lgkmcnt(0)
	s_waitcnt vmcnt(0)
	v_mbcnt_lo_u32_b32 v1, s10, 0
	v_mbcnt_hi_u32_b32 v1, s11, v1
	v_cmp_eq_u32_e32 vcc, 0, v1
	s_and_saveexec_b64 s[12:13], vcc
	s_cbranch_execz .LBB0_258
	s_bcnt1_i32_b64 s0, s[10:11]
	v_mov_b32_e32 v2, s0
	v_mov_b32_e32 v3, 0x3000
	global_atomic_add v2, v3, v2, s[6:7] offset:1024 sc0

; __device__ __forceinline__ unsigned xb_ld(unsigned* p)              { return __hip_atomic_load(p, __ATOMIC_RELAXED, __HIP_MEMORY_SCOPE_AGENT); }
; __device__ __forceinline__ unsigned xb_add(unsigned* p, unsigned v) { return __hip_atomic_fetch_add(p, v, __ATOMIC_RELAXED, __HIP_MEMORY_SCOPE_AGENT); }
; #define XB_SPIN(cond, bar) do { unsigned _sp = 0; while (cond) { __builtin_amdgcn_s_sleep(1); \
;     if ((++_sp & 255u) == 0u) { if (xb_ld(&(bar)[XB_TMO])) break; if (_sp > XB_SPIN_CAP) { atomicAdd(&(bar)[XB_TMO], 1u); break; } } } } while (0)
; __device__ __forceinline__ void xcd_barrier(const XcdBarrier& b) {
;     ...
;             else XB_SPIN(xb_ld(&bar[XB_TOPGEN]) == tg, bar);
;             __builtin_amdgcn_fence(__ATOMIC_ACQUIRE, "agent");
;             xb_add(&bar[XB_XGEN(b.x)], 1u);
.LBB0_272:
	s_or_b64 exec, exec, s[6:7]
	s_mov_b64 s[6:7], exec
	v_mbcnt_lo_u32_b32 v0, s6, 0
	v_mbcnt_hi_u32_b32 v0, s7, v0
	v_cmp_eq_u32_e32 vcc, 0, v0
	s_waitcnt vmcnt(0)
	s_and_saveexec_b64 s[10:11], vcc
	s_cbranch_execz .LBB0_274
	s_bcnt1_i32_b64 s0, s[6:7]
	v_mov_b32_e32 v0, s0
	global_atomic_add v226, v0, s[8:9] offset:1024

; __device__ __forceinline__ unsigned xb_add(unsigned* p, unsigned v) { return __hip_atomic_fetch_add(p, v, __ATOMIC_RELAXED, __HIP_MEMORY_SCOPE_AGENT); }
; __device__ __forceinline__ void xcd_barrier(const XcdBarrier& b) {
;     ...
;         if (old + 1u == (gen + 1u) * nloc) {
;             __builtin_amdgcn_fence(__ATOMIC_RELEASE, "agent");
;             asm volatile("s_waitcnt vmcnt(0)" ::: "memory");
;             const unsigned og = xb_add(&bar[XB_TOP], 1u);
.LBB0_705:
	s_andn2_saveexec_b64 s[10:11], s[10:11]
	s_cbranch_execz .LBB0_725
	s_mov_b64 s[12:13], exec
	buffer_wbl2 sc1
	buffer_inv sc1
	s_waitcnt lgkmcnt(0)
	s_waitcnt vmcnt(0)
	v_mbcnt_lo_u32_b32 v1, s12, 0
	v_mbcnt_hi_u32_b32 v1, s13, v1
	v_cmp_eq_u32_e32 vcc, 0, v1
	s_and_saveexec_b64 s[14:15], vcc
	s_cbranch_execz .LBB0_708
	s_bcnt1_i32_b64 s0, s[12:13]
	v_mov_b32_e32 v2, s0
	v_mov_b32_e32 v3, 0x3000
	global_atomic_add v2, v3, v2, s[6:7] offset:1024 sc0

; __device__ __forceinline__ unsigned xb_ld(unsigned* p)              { return __hip_atomic_load(p, __ATOMIC_RELAXED, __HIP_MEMORY_SCOPE_AGENT); }
; __device__ __forceinline__ unsigned xb_add(unsigned* p, unsigned v) { return __hip_atomic_fetch_add(p, v, __ATOMIC_RELAXED, __HIP_MEMORY_SCOPE_AGENT); }
; #define XB_SPIN(cond, bar) do { unsigned _sp = 0; while (cond) { __builtin_amdgcn_s_sleep(1); \
;     if ((++_sp & 255u) == 0u) { if (xb_ld(&(bar)[XB_TMO])) break; if (_sp > XB_SPIN_CAP) { atomicAdd(&(bar)[XB_TMO], 1u); break; } } } } while (0)
; __device__ __forceinline__ void xcd_barrier(const XcdBarrier& b) {
;     ...
;             else XB_SPIN(xb_ld(&bar[XB_TOPGEN]) == tg, bar);
;             __builtin_amdgcn_fence(__ATOMIC_ACQUIRE, "agent");
;             xb_add(&bar[XB_XGEN(b.x)], 1u);
.LBB0_722:
	s_or_b64 exec, exec, s[6:7]
	s_mov_b64 s[6:7], exec
	v_mbcnt_lo_u32_b32 v0, s6, 0
	v_mbcnt_hi_u32_b32 v0, s7, v0
	v_cmp_eq_u32_e32 vcc, 0, v0
	s_waitcnt vmcnt(0)
	s_and_saveexec_b64 s[12:13], vcc
	s_cbranch_execz .LBB0_724
	s_bcnt1_i32_b64 s0, s[6:7]
	v_mov_b32_e32 v0, s0
	global_atomic_add v226, v0, s[8:9] offset:1024

; __device__ __forceinline__ unsigned xb_add(unsigned* p, unsigned v) { return __hip_atomic_fetch_add(p, v, __ATOMIC_RELAXED, __HIP_MEMORY_SCOPE_AGENT); }
; __device__ __forceinline__ void xcd_barrier(const XcdBarrier& b) {
;     ...
;         if (old + 1u == (gen + 1u) * nloc) {
;             __builtin_amdgcn_fence(__ATOMIC_RELEASE, "agent");
;             asm volatile("s_waitcnt vmcnt(0)" ::: "memory");
;             const unsigned og = xb_add(&bar[XB_TOP], 1u);
.LBB0_1012:
	s_andn2_saveexec_b64 s[2:3], s[10:11]
	s_cbranch_execz .LBB0_1452
	s_mov_b64 s[10:11], exec
	buffer_wbl2 sc1
	buffer_inv sc1
	s_waitcnt lgkmcnt(0)
	s_waitcnt vmcnt(0)
	v_mbcnt_lo_u32_b32 v1, s10, 0
	v_mbcnt_hi_u32_b32 v1, s11, v1
	v_cmp_eq_u32_e32 vcc, 0, v1
	s_and_saveexec_b64 s[12:13], vcc
	s_cbranch_execz .LBB0_1015
	s_bcnt1_i32_b64 s2, s[10:11]
	v_mov_b32_e32 v2, s2
	v_mov_b32_e32 v3, 0x3000
	global_atomic_add v2, v3, v2, s[6:7] offset:1024 sc0

; __device__ __forceinline__ unsigned xb_ld(unsigned* p)              { return __hip_atomic_load(p, __ATOMIC_RELAXED, __HIP_MEMORY_SCOPE_AGENT); }
; __device__ __forceinline__ unsigned xb_add(unsigned* p, unsigned v) { return __hip_atomic_fetch_add(p, v, __ATOMIC_RELAXED, __HIP_MEMORY_SCOPE_AGENT); }
; #define XB_SPIN(cond, bar) do { unsigned _sp = 0; while (cond) { __builtin_amdgcn_s_sleep(1); \
;     if ((++_sp & 255u) == 0u) { if (xb_ld(&(bar)[XB_TMO])) break; if (_sp > XB_SPIN_CAP) { atomicAdd(&(bar)[XB_TMO], 1u); break; } } } } while (0)
; __device__ __forceinline__ void xcd_barrier(const XcdBarrier& b) {
;     ...
;         const unsigned old = xb_add(&bar[XB_XSUB(b.x)], 1u);
;         const unsigned gen = old / nloc;
;         if (old + 1u == (gen + 1u) * nloc) {
;     ...
;             XB_SPIN(xb_ld(&bar[XB_XGEN(b.x)]) == gen, bar);
;             __builtin_amdgcn_fence(__ATOMIC_ACQUIRE, "agent");
;             asm volatile("s_waitcnt vmcnt(0)" ::: "memory");
.LBB0_1129:
	s_or_b64 exec, exec, s[28:29]
	v_cvt_f32_u32_e32 v4, v2
	s_waitcnt vmcnt(0)
	v_readfirstlane_b32 s0, v3
	v_sub_u32_e32 v3, 0, v2
	v_rcp_iflag_f32_e32 v4, v4
	v_add_u32_e32 v5, s0, v1
	v_mul_f32_e32 v4, 0x4f7ffffe, v4
	v_cvt_u32_f32_e32 v4, v4
	v_mul_lo_u32 v1, v3, v4
	v_mul_hi_u32 v1, v4, v1
	v_add_u32_e32 v1, v4, v1
	v_mul_hi_u32 v1, v5, v1
	v_mul_lo_u32 v3, v1, v2
	v_sub_u32_e32 v3, v5, v3
	v_add_u32_e32 v4, 1, v1
	v_cmp_ge_u32_e32 vcc, v3, v2
	s_nop 1
	v_cndmask_b32_e32 v1, v1, v4, vcc
	v_sub_u32_e32 v4, v3, v2
	v_cndmask_b32_e32 v3, v3, v4, vcc
	v_add_u32_e32 v4, 1, v1
	v_cmp_ge_u32_e32 vcc, v3, v2
	v_add_u32_e32 v3, 1, v5
	s_nop 0
	v_cndmask_b32_e32 v1, v1, v4, vcc
	v_mul_lo_u32 v4, v2, v1
	v_add_u32_e32 v2, v4, v2
	v_cmp_ne_u32_e32 vcc, v3, v2
	s_and_saveexec_b64 s[0:1], vcc
	s_xor_b64 s[26:27], exec, s[0:1]
	s_cbranch_execz .LBB0_1143
	buffer_inv sc1
	s_waitcnt lgkmcnt(0)
	global_load_dword v0, v226, s[10:11] offset:1024 sc1
	s_add_u32 s34, s10, 0x2400
	s_addc_u32 s35, s11, 0
	s_waitcnt vmcnt(0)
	v_cmp_eq_u32_e32 vcc, v0, v1
	s_and_saveexec_b64 s[28:29], vcc
	s_cbranch_execz .LBB0_1142
	s_mov_b32 s0, 1
	s_mov_b64 s[36:37], 0
	s_branch .LBB0_1133

; __device__ __forceinline__ unsigned xb_ld(unsigned* p)              { return __hip_atomic_load(p, __ATOMIC_RELAXED, __HIP_MEMORY_SCOPE_AGENT); }
; __device__ __forceinline__ unsigned xb_add(unsigned* p, unsigned v) { return __hip_atomic_fetch_add(p, v, __ATOMIC_RELAXED, __HIP_MEMORY_SCOPE_AGENT); }
; #define XB_SPIN(cond, bar) do { unsigned _sp = 0; while (cond) { __builtin_amdgcn_s_sleep(1); \
;     if ((++_sp & 255u) == 0u) { if (xb_ld(&(bar)[XB_TMO])) break; if (_sp > XB_SPIN_CAP) { atomicAdd(&(bar)[XB_TMO], 1u); break; } } } } while (0)
; __device__ __forceinline__ void xcd_barrier(const XcdBarrier& b) {
;     ...
;         if (old + 1u == (gen + 1u) * nloc) {
;             __builtin_amdgcn_fence(__ATOMIC_RELEASE, "agent");
;             asm volatile("s_waitcnt vmcnt(0)" ::: "memory");
;             const unsigned og = xb_add(&bar[XB_TOP], 1u);
;             const unsigned tg = og / nx;
;             if (og + 1u == (tg + 1u) * nx) xb_add(&bar[XB_TOPGEN], 1u);
;             else XB_SPIN(xb_ld(&bar[XB_TOPGEN]) == tg, bar);
;             __builtin_amdgcn_fence(__ATOMIC_ACQUIRE, "agent");
;             xb_add(&bar[XB_XGEN(b.x)], 1u);
;             asm volatile("s_waitcnt vmcnt(0)" ::: "memory");
;         } else {
;             XB_SPIN(xb_ld(&bar[XB_XGEN(b.x)]) == gen, bar);
;             __builtin_amdgcn_fence(__ATOMIC_ACQUIRE, "agent");
;             asm volatile("s_waitcnt vmcnt(0)" ::: "memory");
.LBB0_1142:
	s_or_b64 exec, exec, s[28:29]
	s_waitcnt vmcnt(0)
	s_waitcnt vmcnt(0)
.LBB0_1143:
	s_andn2_saveexec_b64 s[0:1], s[26:27]
	s_cbranch_execz .LBB0_1163
	s_mov_b64 s[26:27], exec
	buffer_wbl2 sc1
	buffer_inv sc1
	s_waitcnt lgkmcnt(0)
	s_waitcnt vmcnt(0)
	v_mbcnt_lo_u32_b32 v1, s26, 0
	v_mbcnt_hi_u32_b32 v1, s27, v1
	v_cmp_eq_u32_e32 vcc, 0, v1
	s_and_saveexec_b64 s[28:29], vcc
	s_cbranch_execz .LBB0_1146
	s_bcnt1_i32_b64 s0, s[26:27]
	v_mov_b32_e32 v2, s0
	v_mov_b32_e32 v3, 0x3000
	global_atomic_add v2, v3, v2, s[8:9] offset:1024 sc0

; __device__ __forceinline__ unsigned xb_ld(unsigned* p)              { return __hip_atomic_load(p, __ATOMIC_RELAXED, __HIP_MEMORY_SCOPE_AGENT); }
; __device__ __forceinline__ unsigned xb_add(unsigned* p, unsigned v) { return __hip_atomic_fetch_add(p, v, __ATOMIC_RELAXED, __HIP_MEMORY_SCOPE_AGENT); }
; #define XB_SPIN(cond, bar) do { unsigned _sp = 0; while (cond) { __builtin_amdgcn_s_sleep(1); \
;     if ((++_sp & 255u) == 0u) { if (xb_ld(&(bar)[XB_TMO])) break; if (_sp > XB_SPIN_CAP) { atomicAdd(&(bar)[XB_TMO], 1u); break; } } } } while (0)
; __device__ __forceinline__ void xcd_barrier(const XcdBarrier& b) {
;     ...
;             else XB_SPIN(xb_ld(&bar[XB_TOPGEN]) == tg, bar);
;             __builtin_amdgcn_fence(__ATOMIC_ACQUIRE, "agent");
;             xb_add(&bar[XB_XGEN(b.x)], 1u);
.LBB0_1160:
	s_or_b64 exec, exec, s[8:9]
	s_mov_b64 s[8:9], exec
	v_mbcnt_lo_u32_b32 v0, s8, 0
	v_mbcnt_hi_u32_b32 v0, s9, v0
	v_cmp_eq_u32_e32 vcc, 0, v0
	s_waitcnt vmcnt(0)
	s_and_saveexec_b64 s[26:27], vcc
	s_cbranch_execz .LBB0_1162
	s_bcnt1_i32_b64 s0, s[8:9]
	v_mov_b32_e32 v0, s0
	global_atomic_add v226, v0, s[10:11] offset:1024

; __device__ __forceinline__ unsigned xb_ld(unsigned* p)              { return __hip_atomic_load(p, __ATOMIC_RELAXED, __HIP_MEMORY_SCOPE_AGENT); }
; __device__ __forceinline__ unsigned xb_add(unsigned* p, unsigned v) { return __hip_atomic_fetch_add(p, v, __ATOMIC_RELAXED, __HIP_MEMORY_SCOPE_AGENT); }
; #define XB_SPIN(cond, bar) do { unsigned _sp = 0; while (cond) { __builtin_amdgcn_s_sleep(1); \
;     if ((++_sp & 255u) == 0u) { if (xb_ld(&(bar)[XB_TMO])) break; if (_sp > XB_SPIN_CAP) { atomicAdd(&(bar)[XB_TMO], 1u); break; } } } } while (0)
; __device__ __forceinline__ void xcd_barrier(const XcdBarrier& b) {
;     ...
;         const unsigned old = xb_add(&bar[XB_XSUB(b.x)], 1u);
;         const unsigned gen = old / nloc;
;         if (old + 1u == (gen + 1u) * nloc) {
;     ...
;             XB_SPIN(xb_ld(&bar[XB_XGEN(b.x)]) == gen, bar);
;             __builtin_amdgcn_fence(__ATOMIC_ACQUIRE, "agent");
;             asm volatile("s_waitcnt vmcnt(0)" ::: "memory");
.LBB0_1189:
	s_or_b64 exec, exec, s[26:27]
	v_cvt_f32_u32_e32 v4, v2
	s_waitcnt vmcnt(0)
	v_readfirstlane_b32 s0, v3
	v_sub_u32_e32 v3, 0, v2
	v_rcp_iflag_f32_e32 v4, v4
	v_add_u32_e32 v5, s0, v1
	v_mul_f32_e32 v4, 0x4f7ffffe, v4
	v_cvt_u32_f32_e32 v4, v4
	v_mul_lo_u32 v1, v3, v4
	v_mul_hi_u32 v1, v4, v1
	v_add_u32_e32 v1, v4, v1
	v_mul_hi_u32 v1, v5, v1
	v_mul_lo_u32 v3, v1, v2
	v_sub_u32_e32 v3, v5, v3
	v_add_u32_e32 v4, 1, v1
	v_cmp_ge_u32_e32 vcc, v3, v2
	s_nop 1
	v_cndmask_b32_e32 v1, v1, v4, vcc
	v_sub_u32_e32 v4, v3, v2
	v_cndmask_b32_e32 v3, v3, v4, vcc
	v_add_u32_e32 v4, 1, v1
	v_cmp_ge_u32_e32 vcc, v3, v2
	v_add_u32_e32 v3, 1, v5
	s_nop 0
	v_cndmask_b32_e32 v1, v1, v4, vcc
	v_mul_lo_u32 v4, v2, v1
	v_add_u32_e32 v2, v4, v2
	v_cmp_ne_u32_e32 vcc, v3, v2
	s_and_saveexec_b64 s[0:1], vcc
	s_xor_b64 s[12:13], exec, s[0:1]
	s_cbranch_execz .LBB0_1203
	buffer_inv sc1
	s_waitcnt lgkmcnt(0)
	global_load_dword v0, v226, s[10:11] offset:1024 sc1
	s_add_u32 s28, s10, 0x2400
	s_addc_u32 s29, s11, 0
	s_waitcnt vmcnt(0)
	v_cmp_eq_u32_e32 vcc, v0, v1
	s_and_saveexec_b64 s[26:27], vcc
	s_cbranch_execz .LBB0_1202
	s_mov_b32 s0, 1
	s_mov_b64 s[34:35], 0
	s_branch .LBB0_1193

; __device__ __forceinline__ unsigned xb_ld(unsigned* p)              { return __hip_atomic_load(p, __ATOMIC_RELAXED, __HIP_MEMORY_SCOPE_AGENT); }
; __device__ __forceinline__ unsigned xb_add(unsigned* p, unsigned v) { return __hip_atomic_fetch_add(p, v, __ATOMIC_RELAXED, __HIP_MEMORY_SCOPE_AGENT); }
; #define XB_SPIN(cond, bar) do { unsigned _sp = 0; while (cond) { __builtin_amdgcn_s_sleep(1); \
;     if ((++_sp & 255u) == 0u) { if (xb_ld(&(bar)[XB_TMO])) break; if (_sp > XB_SPIN_CAP) { atomicAdd(&(bar)[XB_TMO], 1u); break; } } } } while (0)
; __device__ __forceinline__ void xcd_barrier(const XcdBarrier& b) {
;     ...
;         if (old + 1u == (gen + 1u) * nloc) {
;             __builtin_amdgcn_fence(__ATOMIC_RELEASE, "agent");
;             asm volatile("s_waitcnt vmcnt(0)" ::: "memory");
;             const unsigned og = xb_add(&bar[XB_TOP], 1u);
;             const unsigned tg = og / nx;
;             if (og + 1u == (tg + 1u) * nx) xb_add(&bar[XB_TOPGEN], 1u);
;             else XB_SPIN(xb_ld(&bar[XB_TOPGEN]) == tg, bar);
;             __builtin_amdgcn_fence(__ATOMIC_ACQUIRE, "agent");
;             xb_add(&bar[XB_XGEN(b.x)], 1u);
;             asm volatile("s_waitcnt vmcnt(0)" ::: "memory");
;         } else {
;             XB_SPIN(xb_ld(&bar[XB_XGEN(b.x)]) == gen, bar);
;             __builtin_amdgcn_fence(__ATOMIC_ACQUIRE, "agent");
;             asm volatile("s_waitcnt vmcnt(0)" ::: "memory");
.LBB0_1202:
	s_or_b64 exec, exec, s[26:27]
	s_waitcnt vmcnt(0)
	s_waitcnt vmcnt(0)
.LBB0_1203:
	s_andn2_saveexec_b64 s[0:1], s[12:13]
	s_cbranch_execz .LBB0_1223
	s_mov_b64 s[12:13], exec
	buffer_wbl2 sc1
	buffer_inv sc1
	s_waitcnt lgkmcnt(0)
	s_waitcnt vmcnt(0)
	v_mbcnt_lo_u32_b32 v1, s12, 0
	v_mbcnt_hi_u32_b32 v1, s13, v1
	v_cmp_eq_u32_e32 vcc, 0, v1
	s_and_saveexec_b64 s[26:27], vcc
	s_cbranch_execz .LBB0_1206
	s_bcnt1_i32_b64 s0, s[12:13]
	v_mov_b32_e32 v2, s0
	v_mov_b32_e32 v3, 0x3000
	global_atomic_add v2, v3, v2, s[8:9] offset:1024 sc0

; __device__ __forceinline__ unsigned xb_ld(unsigned* p)              { return __hip_atomic_load(p, __ATOMIC_RELAXED, __HIP_MEMORY_SCOPE_AGENT); }
; __device__ __forceinline__ unsigned xb_add(unsigned* p, unsigned v) { return __hip_atomic_fetch_add(p, v, __ATOMIC_RELAXED, __HIP_MEMORY_SCOPE_AGENT); }
; #define XB_SPIN(cond, bar) do { unsigned _sp = 0; while (cond) { __builtin_amdgcn_s_sleep(1); \
;     if ((++_sp & 255u) == 0u) { if (xb_ld(&(bar)[XB_TMO])) break; if (_sp > XB_SPIN_CAP) { atomicAdd(&(bar)[XB_TMO], 1u); break; } } } } while (0)
; __device__ __forceinline__ void xcd_barrier(const XcdBarrier& b) {
;     ...
;             else XB_SPIN(xb_ld(&bar[XB_TOPGEN]) == tg, bar);
;             __builtin_amdgcn_fence(__ATOMIC_ACQUIRE, "agent");
;             xb_add(&bar[XB_XGEN(b.x)], 1u);
.LBB0_1220:
	s_or_b64 exec, exec, s[8:9]
	s_mov_b64 s[8:9], exec
	v_mbcnt_lo_u32_b32 v0, s8, 0
	v_mbcnt_hi_u32_b32 v0, s9, v0
	v_cmp_eq_u32_e32 vcc, 0, v0
	s_waitcnt vmcnt(0)
	s_and_saveexec_b64 s[12:13], vcc
	s_cbranch_execz .LBB0_1222
	s_bcnt1_i32_b64 s0, s[8:9]
	v_mov_b32_e32 v0, s0
	global_atomic_add v226, v0, s[10:11] offset:1024

; __device__ __forceinline__ unsigned xb_ld(unsigned* p)              { return __hip_atomic_load(p, __ATOMIC_RELAXED, __HIP_MEMORY_SCOPE_AGENT); }
; __device__ __forceinline__ unsigned xb_add(unsigned* p, unsigned v) { return __hip_atomic_fetch_add(p, v, __ATOMIC_RELAXED, __HIP_MEMORY_SCOPE_AGENT); }
; #define XB_SPIN(cond, bar) do { unsigned _sp = 0; while (cond) { __builtin_amdgcn_s_sleep(1); \
;     if ((++_sp & 255u) == 0u) { if (xb_ld(&(bar)[XB_TMO])) break; if (_sp > XB_SPIN_CAP) { atomicAdd(&(bar)[XB_TMO], 1u); break; } } } } while (0)
; __device__ __forceinline__ void xcd_barrier(const XcdBarrier& b) {
;     ...
;         const unsigned old = xb_add(&bar[XB_XSUB(b.x)], 1u);
;         const unsigned gen = old / nloc;
;         if (old + 1u == (gen + 1u) * nloc) {
;     ...
;             XB_SPIN(xb_ld(&bar[XB_XGEN(b.x)]) == gen, bar);
;             __builtin_amdgcn_fence(__ATOMIC_ACQUIRE, "agent");
;             asm volatile("s_waitcnt vmcnt(0)" ::: "memory");
.LBB0_1387:
	s_or_b64 exec, exec, s[12:13]
	v_cvt_f32_u32_e32 v4, v2
	s_waitcnt vmcnt(0)
	v_readfirstlane_b32 s0, v3
	v_sub_u32_e32 v3, 0, v2
	v_rcp_iflag_f32_e32 v4, v4
	v_add_u32_e32 v5, s0, v1
	v_mul_f32_e32 v4, 0x4f7ffffe, v4
	v_cvt_u32_f32_e32 v4, v4
	v_mul_lo_u32 v1, v3, v4
	v_mul_hi_u32 v1, v4, v1
	v_add_u32_e32 v1, v4, v1
	v_mul_hi_u32 v1, v5, v1
	v_mul_lo_u32 v3, v1, v2
	v_sub_u32_e32 v3, v5, v3
	v_add_u32_e32 v4, 1, v1
	v_cmp_ge_u32_e32 vcc, v3, v2
	s_nop 1
	v_cndmask_b32_e32 v1, v1, v4, vcc
	v_sub_u32_e32 v4, v3, v2
	v_cndmask_b32_e32 v3, v3, v4, vcc
	v_add_u32_e32 v4, 1, v1
	v_cmp_ge_u32_e32 vcc, v3, v2
	v_add_u32_e32 v3, 1, v5
	s_nop 0
	v_cndmask_b32_e32 v1, v1, v4, vcc
	v_mul_lo_u32 v4, v2, v1
	v_add_u32_e32 v2, v4, v2
	v_cmp_ne_u32_e32 vcc, v3, v2
	s_and_saveexec_b64 s[0:1], vcc
	s_xor_b64 s[10:11], exec, s[0:1]
	s_cbranch_execz .LBB0_1401
	buffer_inv sc1
	s_waitcnt lgkmcnt(0)
	global_load_dword v0, v226, s[8:9] offset:1024 sc1
	s_add_u32 s26, s8, 0x2400
	s_addc_u32 s27, s9, 0
	s_waitcnt vmcnt(0)
	v_cmp_eq_u32_e32 vcc, v0, v1
	s_and_saveexec_b64 s[12:13], vcc
	s_cbranch_execz .LBB0_1400
	s_mov_b32 s0, 1
	s_mov_b64 s[28:29], 0
	s_branch .LBB0_1391

; __device__ __forceinline__ unsigned xb_add(unsigned* p, unsigned v) { return __hip_atomic_fetch_add(p, v, __ATOMIC_RELAXED, __HIP_MEMORY_SCOPE_AGENT); }
; __device__ __forceinline__ void xcd_barrier(const XcdBarrier& b) {
;     ...
;         if (old + 1u == (gen + 1u) * nloc) {
;             __builtin_amdgcn_fence(__ATOMIC_RELEASE, "agent");
;             asm volatile("s_waitcnt vmcnt(0)" ::: "memory");
;             const unsigned og = xb_add(&bar[XB_TOP], 1u);
.LBB0_1731:
	s_mov_b64 s[10:11], exec
	buffer_wbl2 sc1
	buffer_inv sc1
	s_waitcnt lgkmcnt(0)
	s_waitcnt vmcnt(0)
	v_mbcnt_lo_u32_b32 v1, s10, 0
	v_mbcnt_hi_u32_b32 v1, s11, v1
	v_cmp_eq_u32_e32 vcc, 0, v1
	s_and_saveexec_b64 s[12:13], vcc
	s_cbranch_execz .LBB0_1733
	s_bcnt1_i32_b64 s0, s[10:11]
	v_mov_b32_e32 v2, s0
	v_mov_b32_e32 v3, 0x3000
	global_atomic_add v2, v3, v2, s[6:7] offset:1024 sc0

; __device__ __forceinline__ unsigned xb_ld(unsigned* p)              { return __hip_atomic_load(p, __ATOMIC_RELAXED, __HIP_MEMORY_SCOPE_AGENT); }
; __device__ __forceinline__ unsigned xb_add(unsigned* p, unsigned v) { return __hip_atomic_fetch_add(p, v, __ATOMIC_RELAXED, __HIP_MEMORY_SCOPE_AGENT); }
; #define XB_SPIN(cond, bar) do { unsigned _sp = 0; while (cond) { __builtin_amdgcn_s_sleep(1); \
;     if ((++_sp & 255u) == 0u) { if (xb_ld(&(bar)[XB_TMO])) break; if (_sp > XB_SPIN_CAP) { atomicAdd(&(bar)[XB_TMO], 1u); break; } } } } while (0)
; __device__ __forceinline__ void xcd_barrier(const XcdBarrier& b) {
;     ...
;             else XB_SPIN(xb_ld(&bar[XB_TOPGEN]) == tg, bar);
;             __builtin_amdgcn_fence(__ATOMIC_ACQUIRE, "agent");
;             xb_add(&bar[XB_XGEN(b.x)], 1u);
.LBB0_1747:
	s_or_b64 exec, exec, s[6:7]
	s_mov_b64 s[6:7], exec
	v_mbcnt_lo_u32_b32 v0, s6, 0
	v_mbcnt_hi_u32_b32 v0, s7, v0
	v_cmp_eq_u32_e32 vcc, 0, v0
	s_waitcnt vmcnt(0)
	s_and_saveexec_b64 s[10:11], vcc
	s_cbranch_execnz .LBB0_1748
	s_getpc_b64 s[98:99]
